# nt (streaming) hint on the write-once SwiGLU output stores of P1/P7
# speedup vs baseline: 1.0132x; 1.0132x over previous
; __device__ __forceinline__ unsigned cvt_pk_bf16(float lo, float hi) { unsigned r; asm volatile("v_cvt_pk_bf16_f32 %0, %1, %2" : "=v"(r) : "v"(lo), "v"(hi)); return r; }
;     __device__ __forceinline__ void operator()(Acc& acc, const Unit& u, int wr, int wc, int fr, int fq) const {
;         const int row0 = u.pm * BM + wr * 64 + fr, col0 = u.pn * 128 + wc * 32 + 8 * fq;
; #pragma unroll
;         for (int ai = 0; ai < 2; ++ai)
; #pragma unroll
;             for (int m = 0; m < 4; ++m) {
;                 const int row = row0 + ai * HALF + m * 16;
;                 const float r = rs[u.idx * BM + wr * 64 + fr + ai * HALF + m * 16];
;                 const float c1 = -r * 1.4426950408889634f, r2 = r * r;
;                 f32x4 o[2];
; #pragma unroll
;                 for (int n = 0; n < 2; ++n) {
;                     const f32x4 g = acc[ai][0][m][n], up = acc[ai][1][m][n];
;                     const f32x4 t = g * c1; f32x4 e;
; #pragma unroll
;                     for (int i = 0; i < 4; ++i) e[i] = __builtin_amdgcn_exp2f(t[i]);
;                     const f32x4 d = e + 1.0f; f32x4 q;
; #pragma unroll
;                     for (int i = 0; i < 4; ++i) q[i] = __builtin_amdgcn_rcpf(d[i]);
;                     o[n] = (g * up) * (q * r2);
;                 }
;                 u32x4 w; w.x = cvt_pk_bf16(o[0][0], o[0][1]); w.y = cvt_pk_bf16(o[0][2], o[0][3]); w.z = cvt_pk_bf16(o[1][0], o[1][1]); w.w = cvt_pk_bf16(o[1][2], o[1][3]);
;                 *(u32x4*)(O + (size_t)row * DFF + col0) = w;
.LBB0_610:
	v_lshl_add_u32 v154, s45, 10, v146
	ds_read_b32 v200, v154
	ds_read_b32 v201, v154 offset:64
	ds_read_b32 v202, v154 offset:128
	ds_read_b32 v203, v154 offset:192
	ds_read_b32 v204, v154 offset:512
	ds_read_b32 v205, v154 offset:576
	ds_read_b32 v206, v154 offset:640
	ds_read_b32 v207, v154 offset:704
	v_lshl_or_b32 v156, s47, 7, v147
	v_lshl_add_u32 v151, s20, 8, v144
	v_lshlrev_b32_e32 v156, 1, v156
	v_mov_b32_e32 v198, 1.0
	v_mad_u32_u24 v155, v151, s42, v156
	s_waitcnt lgkmcnt(0)
	v_mul_f32_e32 v158, 0xbfb8aa3b, v200
	v_mul_f32_e32 v160, v200, v200
	v_pk_mul_f32 v[162:163], v[124:125], v[158:159] op_sel_hi:[1,0]
	v_pk_mul_f32 v[164:165], v[126:127], v[158:159] op_sel_hi:[1,0]
	v_pk_mul_f32 v[166:167], v[116:117], v[158:159] op_sel_hi:[1,0]
	v_pk_mul_f32 v[168:169], v[118:119], v[158:159] op_sel_hi:[1,0]
	v_exp_f32_e32 v162, v162
	v_exp_f32_e32 v163, v163
	v_pk_mul_f32 v[120:121], v[124:125], v[120:121]
	v_exp_f32_e32 v164, v164
	v_exp_f32_e32 v165, v165
	v_pk_mul_f32 v[122:123], v[126:127], v[122:123]
	v_exp_f32_e32 v166, v166
	v_exp_f32_e32 v167, v167
	v_pk_mul_f32 v[112:113], v[116:117], v[112:113]
	v_exp_f32_e32 v168, v168
	v_exp_f32_e32 v169, v169
	v_pk_mul_f32 v[114:115], v[118:119], v[114:115]
	v_pk_add_f32 v[162:163], v[162:163], v[198:199] op_sel_hi:[1,0]
	v_pk_add_f32 v[164:165], v[164:165], v[198:199] op_sel_hi:[1,0]
	v_pk_add_f32 v[166:167], v[166:167], v[198:199] op_sel_hi:[1,0]
	v_pk_add_f32 v[168:169], v[168:169], v[198:199] op_sel_hi:[1,0]
	v_rcp_f32_e32 v162, v162
	v_rcp_f32_e32 v163, v163
	v_rcp_f32_e32 v164, v164
	v_rcp_f32_e32 v165, v165
	v_rcp_f32_e32 v166, v166
	v_rcp_f32_e32 v167, v167
	v_rcp_f32_e32 v168, v168
	v_rcp_f32_e32 v169, v169
	v_pk_mul_f32 v[162:163], v[160:161], v[162:163] op_sel_hi:[0,1]
	v_pk_mul_f32 v[164:165], v[160:161], v[164:165] op_sel_hi:[0,1]
	v_pk_mul_f32 v[166:167], v[160:161], v[166:167] op_sel_hi:[0,1]
	v_pk_mul_f32 v[168:169], v[160:161], v[168:169] op_sel_hi:[0,1]
	v_pk_mul_f32 v[120:121], v[120:121], v[162:163]
	v_pk_mul_f32 v[122:123], v[122:123], v[164:165]
	v_pk_mul_f32 v[112:113], v[112:113], v[166:167]
	v_pk_mul_f32 v[114:115], v[114:115], v[168:169]
	v_cvt_pk_bf16_f32 v170, v120, v121
	v_cvt_pk_bf16_f32 v171, v122, v123
	v_cvt_pk_bf16_f32 v172, v112, v113
	v_cvt_pk_bf16_f32 v173, v114, v115
	global_store_dwordx4 v155, v[170:173], s[64:65] nt
	v_mul_f32_e32 v158, 0xbfb8aa3b, v201
	v_mul_f32_e32 v160, v201, v201
	v_pk_mul_f32 v[162:163], v[108:109], v[158:159] op_sel_hi:[1,0]
	v_pk_mul_f32 v[164:165], v[110:111], v[158:159] op_sel_hi:[1,0]
	v_pk_mul_f32 v[166:167], v[100:101], v[158:159] op_sel_hi:[1,0]
	v_pk_mul_f32 v[168:169], v[102:103], v[158:159] op_sel_hi:[1,0]
	v_exp_f32_e32 v162, v162
	v_exp_f32_e32 v163, v163
	v_pk_mul_f32 v[104:105], v[108:109], v[104:105]
	v_exp_f32_e32 v164, v164
	v_exp_f32_e32 v165, v165
	v_pk_mul_f32 v[106:107], v[110:111], v[106:107]
	v_exp_f32_e32 v166, v166
	v_exp_f32_e32 v167, v167
	v_pk_mul_f32 v[96:97], v[100:101], v[96:97]
	v_exp_f32_e32 v168, v168
	v_exp_f32_e32 v169, v169
	v_pk_mul_f32 v[98:99], v[102:103], v[98:99]
	v_pk_add_f32 v[162:163], v[162:163], v[198:199] op_sel_hi:[1,0]
	v_pk_add_f32 v[164:165], v[164:165], v[198:199] op_sel_hi:[1,0]
	v_pk_add_f32 v[166:167], v[166:167], v[198:199] op_sel_hi:[1,0]
	v_pk_add_f32 v[168:169], v[168:169], v[198:199] op_sel_hi:[1,0]
	v_rcp_f32_e32 v162, v162
	v_rcp_f32_e32 v163, v163
	v_rcp_f32_e32 v164, v164
	v_rcp_f32_e32 v165, v165
	v_rcp_f32_e32 v166, v166
	v_rcp_f32_e32 v167, v167
	v_rcp_f32_e32 v168, v168
	v_rcp_f32_e32 v169, v169
	v_pk_mul_f32 v[162:163], v[160:161], v[162:163] op_sel_hi:[0,1]
	v_pk_mul_f32 v[164:165], v[160:161], v[164:165] op_sel_hi:[0,1]
	v_pk_mul_f32 v[166:167], v[160:161], v[166:167] op_sel_hi:[0,1]
	v_pk_mul_f32 v[168:169], v[160:161], v[168:169] op_sel_hi:[0,1]
	v_pk_mul_f32 v[104:105], v[104:105], v[162:163]
	v_pk_mul_f32 v[106:107], v[106:107], v[164:165]
	v_pk_mul_f32 v[96:97], v[96:97], v[166:167]
	v_pk_mul_f32 v[98:99], v[98:99], v[168:169]
	v_cvt_pk_bf16_f32 v176, v104, v105
	v_cvt_pk_bf16_f32 v177, v106, v107
	v_cvt_pk_bf16_f32 v178, v96, v97
	v_cvt_pk_bf16_f32 v179, v98, v99
	v_add_u32_e32 v175, 0x16000, v155
	global_store_dwordx4 v175, v[176:179], s[64:65] nt
	v_mul_f32_e32 v158, 0xbfb8aa3b, v202
	v_mul_f32_e32 v160, v202, v202
	v_pk_mul_f32 v[162:163], v[92:93], v[158:159] op_sel_hi:[1,0]
	v_pk_mul_f32 v[164:165], v[94:95], v[158:159] op_sel_hi:[1,0]
	v_pk_mul_f32 v[166:167], v[84:85], v[158:159] op_sel_hi:[1,0]
	v_pk_mul_f32 v[168:169], v[86:87], v[158:159] op_sel_hi:[1,0]
	v_exp_f32_e32 v162, v162
	v_exp_f32_e32 v163, v163
	v_pk_mul_f32 v[88:89], v[92:93], v[88:89]
	v_exp_f32_e32 v164, v164
	v_exp_f32_e32 v165, v165
	v_pk_mul_f32 v[90:91], v[94:95], v[90:91]
	v_exp_f32_e32 v166, v166
	v_exp_f32_e32 v167, v167
	v_pk_mul_f32 v[80:81], v[84:85], v[80:81]
	v_exp_f32_e32 v168, v168
	v_exp_f32_e32 v169, v169
	v_pk_mul_f32 v[82:83], v[86:87], v[82:83]
	v_pk_add_f32 v[162:163], v[162:163], v[198:199] op_sel_hi:[1,0]
	v_pk_add_f32 v[164:165], v[164:165], v[198:199] op_sel_hi:[1,0]
	v_pk_add_f32 v[166:167], v[166:167], v[198:199] op_sel_hi:[1,0]
	v_pk_add_f32 v[168:169], v[168:169], v[198:199] op_sel_hi:[1,0]
	v_rcp_f32_e32 v162, v162
	v_rcp_f32_e32 v163, v163
	v_rcp_f32_e32 v164, v164
	v_rcp_f32_e32 v165, v165
	v_rcp_f32_e32 v166, v166
	v_rcp_f32_e32 v167, v167
	v_rcp_f32_e32 v168, v168
	v_rcp_f32_e32 v169, v169
	v_pk_mul_f32 v[162:163], v[160:161], v[162:163] op_sel_hi:[0,1]
	v_pk_mul_f32 v[164:165], v[160:161], v[164:165] op_sel_hi:[0,1]
	v_pk_mul_f32 v[166:167], v[160:161], v[166:167] op_sel_hi:[0,1]
	v_pk_mul_f32 v[168:169], v[160:161], v[168:169] op_sel_hi:[0,1]
; __device__ __forceinline__ unsigned cvt_pk_bf16(float lo, float hi) { unsigned r; asm volatile("v_cvt_pk_bf16_f32 %0, %1, %2" : "=v"(r) : "v"(lo), "v"(hi)); return r; }
;     __device__ __forceinline__ void operator()(Acc& acc, const Unit& u, int wr, int wc, int fr, int fq) const {
;     ...
;             for (int m = 0; m < 4; ++m) {
;                 const int row = row0 + ai * HALF + m * 16;
;                 const float r = rs[u.idx * BM + wr * 64 + fr + ai * HALF + m * 16];
;                 const float c1 = -r * 1.4426950408889634f, r2 = r * r;
;                 f32x4 o[2];
; #pragma unroll
;                 for (int n = 0; n < 2; ++n) {
;                     const f32x4 g = acc[ai][0][m][n], up = acc[ai][1][m][n];
;                     const f32x4 t = g * c1; f32x4 e;
; #pragma unroll
;                     for (int i = 0; i < 4; ++i) e[i] = __builtin_amdgcn_exp2f(t[i]);
;                     const f32x4 d = e + 1.0f; f32x4 q;
; #pragma unroll
;                     for (int i = 0; i < 4; ++i) q[i] = __builtin_amdgcn_rcpf(d[i]);
;                     o[n] = (g * up) * (q * r2);
;                 }
;                 u32x4 w; w.x = cvt_pk_bf16(o[0][0], o[0][1]); w.y = cvt_pk_bf16(o[0][2], o[0][3]); w.z = cvt_pk_bf16(o[1][0], o[1][1]); w.w = cvt_pk_bf16(o[1][2], o[1][3]);
;                 *(u32x4*)(O + (size_t)row * DFF + col0) = w;
	v_pk_mul_f32 v[88:89], v[88:89], v[162:163]
	v_pk_mul_f32 v[90:91], v[90:91], v[164:165]
	v_pk_mul_f32 v[80:81], v[80:81], v[166:167]
	v_pk_mul_f32 v[82:83], v[82:83], v[168:169]
	v_cvt_pk_bf16_f32 v170, v88, v89
	v_cvt_pk_bf16_f32 v171, v90, v91
	v_cvt_pk_bf16_f32 v172, v80, v81
	v_cvt_pk_bf16_f32 v173, v82, v83
	v_add_u32_e32 v174, 0x2c000, v155
	global_store_dwordx4 v174, v[170:173], s[64:65] nt
	v_mul_f32_e32 v158, 0xbfb8aa3b, v203
	v_mul_f32_e32 v160, v203, v203
	v_pk_mul_f32 v[162:163], v[76:77], v[158:159] op_sel_hi:[1,0]
	v_pk_mul_f32 v[164:165], v[78:79], v[158:159] op_sel_hi:[1,0]
	v_pk_mul_f32 v[166:167], v[68:69], v[158:159] op_sel_hi:[1,0]
	v_pk_mul_f32 v[168:169], v[70:71], v[158:159] op_sel_hi:[1,0]
	v_exp_f32_e32 v162, v162
	v_exp_f32_e32 v163, v163
	v_pk_mul_f32 v[72:73], v[76:77], v[72:73]
	v_exp_f32_e32 v164, v164
	v_exp_f32_e32 v165, v165
	v_pk_mul_f32 v[74:75], v[78:79], v[74:75]
	v_exp_f32_e32 v166, v166
	v_exp_f32_e32 v167, v167
	v_pk_mul_f32 v[64:65], v[68:69], v[64:65]
	v_exp_f32_e32 v168, v168
	v_exp_f32_e32 v169, v169
	v_pk_mul_f32 v[66:67], v[70:71], v[66:67]
	v_pk_add_f32 v[162:163], v[162:163], v[198:199] op_sel_hi:[1,0]
	v_pk_add_f32 v[164:165], v[164:165], v[198:199] op_sel_hi:[1,0]
	v_pk_add_f32 v[166:167], v[166:167], v[198:199] op_sel_hi:[1,0]
	v_pk_add_f32 v[168:169], v[168:169], v[198:199] op_sel_hi:[1,0]
	v_rcp_f32_e32 v162, v162
	v_rcp_f32_e32 v163, v163
	v_rcp_f32_e32 v164, v164
	v_rcp_f32_e32 v165, v165
	v_rcp_f32_e32 v166, v166
	v_rcp_f32_e32 v167, v167
	v_rcp_f32_e32 v168, v168
	v_rcp_f32_e32 v169, v169
	v_pk_mul_f32 v[162:163], v[160:161], v[162:163] op_sel_hi:[0,1]
	v_pk_mul_f32 v[164:165], v[160:161], v[164:165] op_sel_hi:[0,1]
	v_pk_mul_f32 v[166:167], v[160:161], v[166:167] op_sel_hi:[0,1]
	v_pk_mul_f32 v[168:169], v[160:161], v[168:169] op_sel_hi:[0,1]
	v_pk_mul_f32 v[72:73], v[72:73], v[162:163]
	v_pk_mul_f32 v[74:75], v[74:75], v[164:165]
	v_pk_mul_f32 v[64:65], v[64:65], v[166:167]
	v_pk_mul_f32 v[66:67], v[66:67], v[168:169]
	v_cvt_pk_bf16_f32 v176, v72, v73
	v_cvt_pk_bf16_f32 v177, v74, v75
	v_cvt_pk_bf16_f32 v178, v64, v65
	v_cvt_pk_bf16_f32 v179, v66, v67
	v_add_u32_e32 v175, 0x42000, v155
	global_store_dwordx4 v175, v[176:179], s[64:65] nt
	v_mul_f32_e32 v158, 0xbfb8aa3b, v204
	v_mul_f32_e32 v160, v204, v204
	v_pk_mul_f32 v[162:163], v[60:61], v[158:159] op_sel_hi:[1,0]
	v_pk_mul_f32 v[164:165], v[62:63], v[158:159] op_sel_hi:[1,0]
	v_pk_mul_f32 v[166:167], v[52:53], v[158:159] op_sel_hi:[1,0]
	v_pk_mul_f32 v[168:169], v[54:55], v[158:159] op_sel_hi:[1,0]
	v_exp_f32_e32 v162, v162
	v_exp_f32_e32 v163, v163
	v_pk_mul_f32 v[56:57], v[60:61], v[56:57]
	v_exp_f32_e32 v164, v164
	v_exp_f32_e32 v165, v165
	v_pk_mul_f32 v[58:59], v[62:63], v[58:59]
	v_exp_f32_e32 v166, v166
	v_exp_f32_e32 v167, v167
	v_pk_mul_f32 v[48:49], v[52:53], v[48:49]
	v_exp_f32_e32 v168, v168
	v_exp_f32_e32 v169, v169
	v_pk_mul_f32 v[50:51], v[54:55], v[50:51]
	v_pk_add_f32 v[162:163], v[162:163], v[198:199] op_sel_hi:[1,0]
	v_pk_add_f32 v[164:165], v[164:165], v[198:199] op_sel_hi:[1,0]
	v_pk_add_f32 v[166:167], v[166:167], v[198:199] op_sel_hi:[1,0]
	v_pk_add_f32 v[168:169], v[168:169], v[198:199] op_sel_hi:[1,0]
	v_rcp_f32_e32 v162, v162
	v_rcp_f32_e32 v163, v163
	v_rcp_f32_e32 v164, v164
	v_rcp_f32_e32 v165, v165
	v_rcp_f32_e32 v166, v166
	v_rcp_f32_e32 v167, v167
	v_rcp_f32_e32 v168, v168
	v_rcp_f32_e32 v169, v169
	v_pk_mul_f32 v[162:163], v[160:161], v[162:163] op_sel_hi:[0,1]
	v_pk_mul_f32 v[164:165], v[160:161], v[164:165] op_sel_hi:[0,1]
	v_pk_mul_f32 v[166:167], v[160:161], v[166:167] op_sel_hi:[0,1]
	v_pk_mul_f32 v[168:169], v[160:161], v[168:169] op_sel_hi:[0,1]
	v_pk_mul_f32 v[56:57], v[56:57], v[162:163]
	v_pk_mul_f32 v[58:59], v[58:59], v[164:165]
	v_pk_mul_f32 v[48:49], v[48:49], v[166:167]
	v_pk_mul_f32 v[50:51], v[50:51], v[168:169]
	v_cvt_pk_bf16_f32 v170, v56, v57
	v_cvt_pk_bf16_f32 v171, v58, v59
	v_cvt_pk_bf16_f32 v172, v48, v49
	v_cvt_pk_bf16_f32 v173, v50, v51
	v_add_u32_e32 v174, 0xb0000, v155
	global_store_dwordx4 v174, v[170:173], s[64:65] nt
	v_mul_f32_e32 v158, 0xbfb8aa3b, v205
	v_mul_f32_e32 v160, v205, v205
	v_pk_mul_f32 v[162:163], v[44:45], v[158:159] op_sel_hi:[1,0]
	v_pk_mul_f32 v[164:165], v[46:47], v[158:159] op_sel_hi:[1,0]
	v_pk_mul_f32 v[166:167], v[36:37], v[158:159] op_sel_hi:[1,0]
	v_pk_mul_f32 v[168:169], v[38:39], v[158:159] op_sel_hi:[1,0]
	v_exp_f32_e32 v162, v162
	v_exp_f32_e32 v163, v163
	v_pk_mul_f32 v[40:41], v[44:45], v[40:41]
	v_exp_f32_e32 v164, v164
	v_exp_f32_e32 v165, v165
	v_pk_mul_f32 v[42:43], v[46:47], v[42:43]
	v_exp_f32_e32 v166, v166
	v_exp_f32_e32 v167, v167
	v_pk_mul_f32 v[32:33], v[36:37], v[32:33]
	v_exp_f32_e32 v168, v168
	v_exp_f32_e32 v169, v169
	v_pk_mul_f32 v[34:35], v[38:39], v[34:35]
	v_pk_add_f32 v[162:163], v[162:163], v[198:199] op_sel_hi:[1,0]
; __device__ __forceinline__ unsigned cvt_pk_bf16(float lo, float hi) { unsigned r; asm volatile("v_cvt_pk_bf16_f32 %0, %1, %2" : "=v"(r) : "v"(lo), "v"(hi)); return r; }
; #define PG8_BAR __builtin_amdgcn_s_barrier()
;     __device__ __forceinline__ void operator()(Acc& acc, const Unit& u, int wr, int wc, int fr, int fq) const {
;     ...
;             for (int m = 0; m < 4; ++m) {
;                 const int row = row0 + ai * HALF + m * 16;
;                 const float r = rs[u.idx * BM + wr * 64 + fr + ai * HALF + m * 16];
;                 const float c1 = -r * 1.4426950408889634f, r2 = r * r;
;                 f32x4 o[2];
; #pragma unroll
;                 for (int n = 0; n < 2; ++n) {
;                     const f32x4 g = acc[ai][0][m][n], up = acc[ai][1][m][n];
;                     const f32x4 t = g * c1; f32x4 e;
; #pragma unroll
;                     for (int i = 0; i < 4; ++i) e[i] = __builtin_amdgcn_exp2f(t[i]);
;                     const f32x4 d = e + 1.0f; f32x4 q;
; #pragma unroll
;                     for (int i = 0; i < 4; ++i) q[i] = __builtin_amdgcn_rcpf(d[i]);
;                     o[n] = (g * up) * (q * r2);
;                 }
;                 u32x4 w; w.x = cvt_pk_bf16(o[0][0], o[0][1]); w.y = cvt_pk_bf16(o[0][2], o[0][3]); w.z = cvt_pk_bf16(o[1][0], o[1][1]); w.w = cvt_pk_bf16(o[1][2], o[1][3]);
;                 *(u32x4*)(O + (size_t)row * DFF + col0) = w;
; template <class Epi, class Sched, bool ALIGN_EPI>
; __device__ __forceinline__ void gemm_phase(LAS unsigned char* lds, const Gemm g, const Sched& S, const Epi& E) {
;     ...
;         if (!has_next) break;
; #pragma unroll
;         for (int a = 0; a < 2; ++a)
; #pragma unroll
;             for (int b = 0; b < 2; ++b)
; #pragma unroll
;                 for (int m = 0; m < 4; ++m)
; #pragma unroll
;                     for (int n = 0; n < 2; ++n) acc[a][b][m][n] = (f32x4){0.f, 0.f, 0.f, 0.f};
;         cur = nxt; cA = nA; cB = nB; ++ui;
;         if constexpr (ALIGN_EPI) { if (wr == 1) PG8_BAR; }
	v_pk_add_f32 v[164:165], v[164:165], v[198:199] op_sel_hi:[1,0]
	v_pk_add_f32 v[166:167], v[166:167], v[198:199] op_sel_hi:[1,0]
	v_pk_add_f32 v[168:169], v[168:169], v[198:199] op_sel_hi:[1,0]
	v_rcp_f32_e32 v162, v162
	v_rcp_f32_e32 v163, v163
	v_rcp_f32_e32 v164, v164
	v_rcp_f32_e32 v165, v165
	v_rcp_f32_e32 v166, v166
	v_rcp_f32_e32 v167, v167
	v_rcp_f32_e32 v168, v168
	v_rcp_f32_e32 v169, v169
	v_pk_mul_f32 v[162:163], v[160:161], v[162:163] op_sel_hi:[0,1]
	v_pk_mul_f32 v[164:165], v[160:161], v[164:165] op_sel_hi:[0,1]
	v_pk_mul_f32 v[166:167], v[160:161], v[166:167] op_sel_hi:[0,1]
	v_pk_mul_f32 v[168:169], v[160:161], v[168:169] op_sel_hi:[0,1]
	v_pk_mul_f32 v[40:41], v[40:41], v[162:163]
	v_pk_mul_f32 v[42:43], v[42:43], v[164:165]
	v_pk_mul_f32 v[32:33], v[32:33], v[166:167]
	v_pk_mul_f32 v[34:35], v[34:35], v[168:169]
	v_cvt_pk_bf16_f32 v176, v40, v41
	v_cvt_pk_bf16_f32 v177, v42, v43
	v_cvt_pk_bf16_f32 v178, v32, v33
	v_cvt_pk_bf16_f32 v179, v34, v35
	v_add_u32_e32 v175, 0xc6000, v155
	global_store_dwordx4 v175, v[176:179], s[64:65] nt
	v_mul_f32_e32 v158, 0xbfb8aa3b, v206
	v_mul_f32_e32 v160, v206, v206
	v_pk_mul_f32 v[162:163], v[28:29], v[158:159] op_sel_hi:[1,0]
	v_pk_mul_f32 v[164:165], v[30:31], v[158:159] op_sel_hi:[1,0]
	v_pk_mul_f32 v[166:167], v[20:21], v[158:159] op_sel_hi:[1,0]
	v_pk_mul_f32 v[168:169], v[22:23], v[158:159] op_sel_hi:[1,0]
	v_exp_f32_e32 v162, v162
	v_exp_f32_e32 v163, v163
	v_pk_mul_f32 v[24:25], v[28:29], v[24:25]
	v_exp_f32_e32 v164, v164
	v_exp_f32_e32 v165, v165
	v_pk_mul_f32 v[26:27], v[30:31], v[26:27]
	v_exp_f32_e32 v166, v166
	v_exp_f32_e32 v167, v167
	v_pk_mul_f32 v[16:17], v[20:21], v[16:17]
	v_exp_f32_e32 v168, v168
	v_exp_f32_e32 v169, v169
	v_pk_mul_f32 v[18:19], v[22:23], v[18:19]
	v_pk_add_f32 v[162:163], v[162:163], v[198:199] op_sel_hi:[1,0]
	v_pk_add_f32 v[164:165], v[164:165], v[198:199] op_sel_hi:[1,0]
	v_pk_add_f32 v[166:167], v[166:167], v[198:199] op_sel_hi:[1,0]
	v_pk_add_f32 v[168:169], v[168:169], v[198:199] op_sel_hi:[1,0]
	v_rcp_f32_e32 v162, v162
	v_rcp_f32_e32 v163, v163
	v_rcp_f32_e32 v164, v164
	v_rcp_f32_e32 v165, v165
	v_rcp_f32_e32 v166, v166
	v_rcp_f32_e32 v167, v167
	v_rcp_f32_e32 v168, v168
	v_rcp_f32_e32 v169, v169
	v_pk_mul_f32 v[162:163], v[160:161], v[162:163] op_sel_hi:[0,1]
	v_pk_mul_f32 v[164:165], v[160:161], v[164:165] op_sel_hi:[0,1]
	v_pk_mul_f32 v[166:167], v[160:161], v[166:167] op_sel_hi:[0,1]
	v_pk_mul_f32 v[168:169], v[160:161], v[168:169] op_sel_hi:[0,1]
	v_pk_mul_f32 v[24:25], v[24:25], v[162:163]
	v_pk_mul_f32 v[26:27], v[26:27], v[164:165]
	v_pk_mul_f32 v[16:17], v[16:17], v[166:167]
	v_pk_mul_f32 v[18:19], v[18:19], v[168:169]
	v_cvt_pk_bf16_f32 v170, v24, v25
	v_cvt_pk_bf16_f32 v171, v26, v27
	v_cvt_pk_bf16_f32 v172, v16, v17
	v_cvt_pk_bf16_f32 v173, v18, v19
	v_add_u32_e32 v174, 0xdc000, v155
	global_store_dwordx4 v174, v[170:173], s[64:65] nt
	v_mul_f32_e32 v158, 0xbfb8aa3b, v207
	v_mul_f32_e32 v160, v207, v207
	v_pk_mul_f32 v[162:163], v[12:13], v[158:159] op_sel_hi:[1,0]
	v_pk_mul_f32 v[164:165], v[14:15], v[158:159] op_sel_hi:[1,0]
	v_pk_mul_f32 v[166:167], v[4:5], v[158:159] op_sel_hi:[1,0]
	v_pk_mul_f32 v[168:169], v[6:7], v[158:159] op_sel_hi:[1,0]
	v_exp_f32_e32 v162, v162
	v_exp_f32_e32 v163, v163
	v_pk_mul_f32 v[8:9], v[12:13], v[8:9]
	v_exp_f32_e32 v164, v164
	v_exp_f32_e32 v165, v165
	v_pk_mul_f32 v[10:11], v[14:15], v[10:11]
	v_exp_f32_e32 v166, v166
	v_exp_f32_e32 v167, v167
	v_pk_mul_f32 v[0:1], v[4:5], v[0:1]
	v_exp_f32_e32 v168, v168
	v_exp_f32_e32 v169, v169
	v_pk_mul_f32 v[2:3], v[6:7], v[2:3]
	v_pk_add_f32 v[162:163], v[162:163], v[198:199] op_sel_hi:[1,0]
	v_pk_add_f32 v[164:165], v[164:165], v[198:199] op_sel_hi:[1,0]
	v_pk_add_f32 v[166:167], v[166:167], v[198:199] op_sel_hi:[1,0]
	v_pk_add_f32 v[168:169], v[168:169], v[198:199] op_sel_hi:[1,0]
	v_rcp_f32_e32 v162, v162
	v_rcp_f32_e32 v163, v163
	v_rcp_f32_e32 v164, v164
	v_rcp_f32_e32 v165, v165
	v_rcp_f32_e32 v166, v166
	v_rcp_f32_e32 v167, v167
	v_rcp_f32_e32 v168, v168
	v_rcp_f32_e32 v169, v169
	v_pk_mul_f32 v[162:163], v[160:161], v[162:163] op_sel_hi:[0,1]
	v_pk_mul_f32 v[164:165], v[160:161], v[164:165] op_sel_hi:[0,1]
	v_pk_mul_f32 v[166:167], v[160:161], v[166:167] op_sel_hi:[0,1]
	v_pk_mul_f32 v[168:169], v[160:161], v[168:169] op_sel_hi:[0,1]
	v_pk_mul_f32 v[8:9], v[8:9], v[162:163]
	v_pk_mul_f32 v[10:11], v[10:11], v[164:165]
	v_pk_mul_f32 v[0:1], v[0:1], v[166:167]
	v_pk_mul_f32 v[2:3], v[2:3], v[168:169]
	v_cvt_pk_bf16_f32 v176, v8, v9
	v_cvt_pk_bf16_f32 v177, v10, v11
	v_cvt_pk_bf16_f32 v178, v0, v1
	v_cvt_pk_bf16_f32 v179, v2, v3
	v_add_u32_e32 v175, 0xf2000, v155
	global_store_dwordx4 v175, v[176:179], s[64:65] nt
	s_andn2_b64 vcc, exec, s[2:3]
	s_mov_b64 s[2:3], -1
	s_mov_b32 s101, 1
	s_cbranch_vccnz .LBB0_603
	s_andn2_b64 vcc, exec, s[6:7]
	s_cbranch_vccnz .LBB0_602
	s_barrier
	s_branch .LBB0_602

; __device__ __forceinline__ unsigned cvt_pk_bf16(float lo, float hi) { unsigned r; asm volatile("v_cvt_pk_bf16_f32 %0, %1, %2" : "=v"(r) : "v"(lo), "v"(hi)); return r; }
;     __device__ __forceinline__ void operator()(Acc& acc, const Unit& u, int wr, int wc, int fr, int fq) const {
;         const int row0 = u.pm * BM + wr * 64 + fr, col0 = u.pn * 128 + wc * 32 + 8 * fq;
; #pragma unroll
;         for (int ai = 0; ai < 2; ++ai)
; #pragma unroll
;             for (int m = 0; m < 4; ++m) {
;                 const int row = row0 + ai * HALF + m * 16;
;                 const float r = rs[u.idx * BM + wr * 64 + fr + ai * HALF + m * 16];
;                 const float c1 = -r * 1.4426950408889634f, r2 = r * r;
;                 f32x4 o[2];
; #pragma unroll
;                 for (int n = 0; n < 2; ++n) {
;                     const f32x4 g = acc[ai][0][m][n], up = acc[ai][1][m][n];
;                     const f32x4 t = g * c1; f32x4 e;
; #pragma unroll
;                     for (int i = 0; i < 4; ++i) e[i] = __builtin_amdgcn_exp2f(t[i]);
;                     const f32x4 d = e + 1.0f; f32x4 q;
; #pragma unroll
;                     for (int i = 0; i < 4; ++i) q[i] = __builtin_amdgcn_rcpf(d[i]);
;                     o[n] = (g * up) * (q * r2);
;                 }
;                 u32x4 w; w.x = cvt_pk_bf16(o[0][0], o[0][1]); w.y = cvt_pk_bf16(o[0][2], o[0][3]); w.z = cvt_pk_bf16(o[1][0], o[1][1]); w.w = cvt_pk_bf16(o[1][2], o[1][3]);
;                 *(u32x4*)(O + (size_t)row * DFF + col0) = w;
.LBB0_1616:
	v_lshl_add_u32 v154, s43, 10, v146
	ds_read_b32 v200, v154
	ds_read_b32 v201, v154 offset:64
	ds_read_b32 v202, v154 offset:128
	ds_read_b32 v203, v154 offset:192
	ds_read_b32 v204, v154 offset:512
	ds_read_b32 v205, v154 offset:576
	ds_read_b32 v206, v154 offset:640
	ds_read_b32 v207, v154 offset:704
	v_lshl_or_b32 v156, s44, 7, v147
	v_lshl_add_u32 v151, s18, 8, v144
	v_lshlrev_b32_e32 v156, 1, v156
	v_mov_b32_e32 v198, 1.0
	v_mad_u32_u24 v155, v151, s40, v156
	s_waitcnt lgkmcnt(0)
	v_mul_f32_e32 v158, 0xbfb8aa3b, v200
	v_mul_f32_e32 v160, v200, v200
	v_pk_mul_f32 v[162:163], v[124:125], v[158:159] op_sel_hi:[1,0]
	v_pk_mul_f32 v[164:165], v[126:127], v[158:159] op_sel_hi:[1,0]
	v_pk_mul_f32 v[166:167], v[116:117], v[158:159] op_sel_hi:[1,0]
	v_pk_mul_f32 v[168:169], v[118:119], v[158:159] op_sel_hi:[1,0]
	v_exp_f32_e32 v162, v162
	v_exp_f32_e32 v163, v163
	v_pk_mul_f32 v[120:121], v[124:125], v[120:121]
	v_exp_f32_e32 v164, v164
	v_exp_f32_e32 v165, v165
	v_pk_mul_f32 v[122:123], v[126:127], v[122:123]
	v_exp_f32_e32 v166, v166
	v_exp_f32_e32 v167, v167
	v_pk_mul_f32 v[112:113], v[116:117], v[112:113]
	v_exp_f32_e32 v168, v168
	v_exp_f32_e32 v169, v169
	v_pk_mul_f32 v[114:115], v[118:119], v[114:115]
	v_pk_add_f32 v[162:163], v[162:163], v[198:199] op_sel_hi:[1,0]
	v_pk_add_f32 v[164:165], v[164:165], v[198:199] op_sel_hi:[1,0]
	v_pk_add_f32 v[166:167], v[166:167], v[198:199] op_sel_hi:[1,0]
	v_pk_add_f32 v[168:169], v[168:169], v[198:199] op_sel_hi:[1,0]
	v_rcp_f32_e32 v162, v162
	v_rcp_f32_e32 v163, v163
	v_rcp_f32_e32 v164, v164
	v_rcp_f32_e32 v165, v165
	v_rcp_f32_e32 v166, v166
	v_rcp_f32_e32 v167, v167
	v_rcp_f32_e32 v168, v168
	v_rcp_f32_e32 v169, v169
	v_pk_mul_f32 v[162:163], v[160:161], v[162:163] op_sel_hi:[0,1]
	v_pk_mul_f32 v[164:165], v[160:161], v[164:165] op_sel_hi:[0,1]
	v_pk_mul_f32 v[166:167], v[160:161], v[166:167] op_sel_hi:[0,1]
	v_pk_mul_f32 v[168:169], v[160:161], v[168:169] op_sel_hi:[0,1]
	v_pk_mul_f32 v[120:121], v[120:121], v[162:163]
	v_pk_mul_f32 v[122:123], v[122:123], v[164:165]
	v_pk_mul_f32 v[112:113], v[112:113], v[166:167]
	v_pk_mul_f32 v[114:115], v[114:115], v[168:169]
	v_cvt_pk_bf16_f32 v170, v120, v121
	v_cvt_pk_bf16_f32 v171, v122, v123
	v_cvt_pk_bf16_f32 v172, v112, v113
	v_cvt_pk_bf16_f32 v173, v114, v115
	global_store_dwordx4 v155, v[170:173], s[64:65] nt
	v_mul_f32_e32 v158, 0xbfb8aa3b, v201
	v_mul_f32_e32 v160, v201, v201
	v_pk_mul_f32 v[162:163], v[108:109], v[158:159] op_sel_hi:[1,0]
	v_pk_mul_f32 v[164:165], v[110:111], v[158:159] op_sel_hi:[1,0]
	v_pk_mul_f32 v[166:167], v[100:101], v[158:159] op_sel_hi:[1,0]
	v_pk_mul_f32 v[168:169], v[102:103], v[158:159] op_sel_hi:[1,0]
	v_exp_f32_e32 v162, v162
	v_exp_f32_e32 v163, v163
	v_pk_mul_f32 v[104:105], v[108:109], v[104:105]
	v_exp_f32_e32 v164, v164
	v_exp_f32_e32 v165, v165
	v_pk_mul_f32 v[106:107], v[110:111], v[106:107]
	v_exp_f32_e32 v166, v166
	v_exp_f32_e32 v167, v167
	v_pk_mul_f32 v[96:97], v[100:101], v[96:97]
	v_exp_f32_e32 v168, v168
	v_exp_f32_e32 v169, v169
	v_pk_mul_f32 v[98:99], v[102:103], v[98:99]
	v_pk_add_f32 v[162:163], v[162:163], v[198:199] op_sel_hi:[1,0]
	v_pk_add_f32 v[164:165], v[164:165], v[198:199] op_sel_hi:[1,0]
	v_pk_add_f32 v[166:167], v[166:167], v[198:199] op_sel_hi:[1,0]
	v_pk_add_f32 v[168:169], v[168:169], v[198:199] op_sel_hi:[1,0]
	v_rcp_f32_e32 v162, v162
	v_rcp_f32_e32 v163, v163
	v_rcp_f32_e32 v164, v164
	v_rcp_f32_e32 v165, v165
	v_rcp_f32_e32 v166, v166
	v_rcp_f32_e32 v167, v167
	v_rcp_f32_e32 v168, v168
	v_rcp_f32_e32 v169, v169
	v_pk_mul_f32 v[162:163], v[160:161], v[162:163] op_sel_hi:[0,1]
	v_pk_mul_f32 v[164:165], v[160:161], v[164:165] op_sel_hi:[0,1]
	v_pk_mul_f32 v[166:167], v[160:161], v[166:167] op_sel_hi:[0,1]
	v_pk_mul_f32 v[168:169], v[160:161], v[168:169] op_sel_hi:[0,1]
	v_pk_mul_f32 v[104:105], v[104:105], v[162:163]
	v_pk_mul_f32 v[106:107], v[106:107], v[164:165]
	v_pk_mul_f32 v[96:97], v[96:97], v[166:167]
	v_pk_mul_f32 v[98:99], v[98:99], v[168:169]
	v_cvt_pk_bf16_f32 v176, v104, v105
	v_cvt_pk_bf16_f32 v177, v106, v107
	v_cvt_pk_bf16_f32 v178, v96, v97
	v_cvt_pk_bf16_f32 v179, v98, v99
	v_add_u32_e32 v175, 0x16000, v155
	global_store_dwordx4 v175, v[176:179], s[64:65] nt
	v_mul_f32_e32 v158, 0xbfb8aa3b, v202
	v_mul_f32_e32 v160, v202, v202
	v_pk_mul_f32 v[162:163], v[92:93], v[158:159] op_sel_hi:[1,0]
	v_pk_mul_f32 v[164:165], v[94:95], v[158:159] op_sel_hi:[1,0]
	v_pk_mul_f32 v[166:167], v[84:85], v[158:159] op_sel_hi:[1,0]
	v_pk_mul_f32 v[168:169], v[86:87], v[158:159] op_sel_hi:[1,0]
	v_exp_f32_e32 v162, v162
	v_exp_f32_e32 v163, v163
	v_pk_mul_f32 v[88:89], v[92:93], v[88:89]
	v_exp_f32_e32 v164, v164
	v_exp_f32_e32 v165, v165
	v_pk_mul_f32 v[90:91], v[94:95], v[90:91]
	v_exp_f32_e32 v166, v166
	v_exp_f32_e32 v167, v167
	v_pk_mul_f32 v[80:81], v[84:85], v[80:81]
	v_exp_f32_e32 v168, v168
	v_exp_f32_e32 v169, v169
	v_pk_mul_f32 v[82:83], v[86:87], v[82:83]
	v_pk_add_f32 v[162:163], v[162:163], v[198:199] op_sel_hi:[1,0]
	v_pk_add_f32 v[164:165], v[164:165], v[198:199] op_sel_hi:[1,0]
	v_pk_add_f32 v[166:167], v[166:167], v[198:199] op_sel_hi:[1,0]
	v_pk_add_f32 v[168:169], v[168:169], v[198:199] op_sel_hi:[1,0]
	v_rcp_f32_e32 v162, v162
	v_rcp_f32_e32 v163, v163
	v_rcp_f32_e32 v164, v164
	v_rcp_f32_e32 v165, v165
	v_rcp_f32_e32 v166, v166
	v_rcp_f32_e32 v167, v167
	v_rcp_f32_e32 v168, v168
	v_rcp_f32_e32 v169, v169
	v_pk_mul_f32 v[162:163], v[160:161], v[162:163] op_sel_hi:[0,1]
	v_pk_mul_f32 v[164:165], v[160:161], v[164:165] op_sel_hi:[0,1]
	v_pk_mul_f32 v[166:167], v[160:161], v[166:167] op_sel_hi:[0,1]
	v_pk_mul_f32 v[168:169], v[160:161], v[168:169] op_sel_hi:[0,1]
; __device__ __forceinline__ unsigned cvt_pk_bf16(float lo, float hi) { unsigned r; asm volatile("v_cvt_pk_bf16_f32 %0, %1, %2" : "=v"(r) : "v"(lo), "v"(hi)); return r; }
;     __device__ __forceinline__ void operator()(Acc& acc, const Unit& u, int wr, int wc, int fr, int fq) const {
;     ...
;             for (int m = 0; m < 4; ++m) {
;                 const int row = row0 + ai * HALF + m * 16;
;                 const float r = rs[u.idx * BM + wr * 64 + fr + ai * HALF + m * 16];
;                 const float c1 = -r * 1.4426950408889634f, r2 = r * r;
;                 f32x4 o[2];
; #pragma unroll
;                 for (int n = 0; n < 2; ++n) {
;                     const f32x4 g = acc[ai][0][m][n], up = acc[ai][1][m][n];
;                     const f32x4 t = g * c1; f32x4 e;
; #pragma unroll
;                     for (int i = 0; i < 4; ++i) e[i] = __builtin_amdgcn_exp2f(t[i]);
;                     const f32x4 d = e + 1.0f; f32x4 q;
; #pragma unroll
;                     for (int i = 0; i < 4; ++i) q[i] = __builtin_amdgcn_rcpf(d[i]);
;                     o[n] = (g * up) * (q * r2);
;                 }
;                 u32x4 w; w.x = cvt_pk_bf16(o[0][0], o[0][1]); w.y = cvt_pk_bf16(o[0][2], o[0][3]); w.z = cvt_pk_bf16(o[1][0], o[1][1]); w.w = cvt_pk_bf16(o[1][2], o[1][3]);
;                 *(u32x4*)(O + (size_t)row * DFF + col0) = w;
	v_pk_mul_f32 v[88:89], v[88:89], v[162:163]
	v_pk_mul_f32 v[90:91], v[90:91], v[164:165]
	v_pk_mul_f32 v[80:81], v[80:81], v[166:167]
	v_pk_mul_f32 v[82:83], v[82:83], v[168:169]
	v_cvt_pk_bf16_f32 v170, v88, v89
	v_cvt_pk_bf16_f32 v171, v90, v91
	v_cvt_pk_bf16_f32 v172, v80, v81
	v_cvt_pk_bf16_f32 v173, v82, v83
	v_add_u32_e32 v174, 0x2c000, v155
	global_store_dwordx4 v174, v[170:173], s[64:65] nt
	v_mul_f32_e32 v158, 0xbfb8aa3b, v203
	v_mul_f32_e32 v160, v203, v203
	v_pk_mul_f32 v[162:163], v[76:77], v[158:159] op_sel_hi:[1,0]
	v_pk_mul_f32 v[164:165], v[78:79], v[158:159] op_sel_hi:[1,0]
	v_pk_mul_f32 v[166:167], v[68:69], v[158:159] op_sel_hi:[1,0]
	v_pk_mul_f32 v[168:169], v[70:71], v[158:159] op_sel_hi:[1,0]
	v_exp_f32_e32 v162, v162
	v_exp_f32_e32 v163, v163
	v_pk_mul_f32 v[72:73], v[76:77], v[72:73]
	v_exp_f32_e32 v164, v164
	v_exp_f32_e32 v165, v165
	v_pk_mul_f32 v[74:75], v[78:79], v[74:75]
	v_exp_f32_e32 v166, v166
	v_exp_f32_e32 v167, v167
	v_pk_mul_f32 v[64:65], v[68:69], v[64:65]
	v_exp_f32_e32 v168, v168
	v_exp_f32_e32 v169, v169
	v_pk_mul_f32 v[66:67], v[70:71], v[66:67]
	v_pk_add_f32 v[162:163], v[162:163], v[198:199] op_sel_hi:[1,0]
	v_pk_add_f32 v[164:165], v[164:165], v[198:199] op_sel_hi:[1,0]
	v_pk_add_f32 v[166:167], v[166:167], v[198:199] op_sel_hi:[1,0]
	v_pk_add_f32 v[168:169], v[168:169], v[198:199] op_sel_hi:[1,0]
	v_rcp_f32_e32 v162, v162
	v_rcp_f32_e32 v163, v163
	v_rcp_f32_e32 v164, v164
	v_rcp_f32_e32 v165, v165
	v_rcp_f32_e32 v166, v166
	v_rcp_f32_e32 v167, v167
	v_rcp_f32_e32 v168, v168
	v_rcp_f32_e32 v169, v169
	v_pk_mul_f32 v[162:163], v[160:161], v[162:163] op_sel_hi:[0,1]
	v_pk_mul_f32 v[164:165], v[160:161], v[164:165] op_sel_hi:[0,1]
	v_pk_mul_f32 v[166:167], v[160:161], v[166:167] op_sel_hi:[0,1]
	v_pk_mul_f32 v[168:169], v[160:161], v[168:169] op_sel_hi:[0,1]
	v_pk_mul_f32 v[72:73], v[72:73], v[162:163]
	v_pk_mul_f32 v[74:75], v[74:75], v[164:165]
	v_pk_mul_f32 v[64:65], v[64:65], v[166:167]
	v_pk_mul_f32 v[66:67], v[66:67], v[168:169]
	v_cvt_pk_bf16_f32 v176, v72, v73
	v_cvt_pk_bf16_f32 v177, v74, v75
	v_cvt_pk_bf16_f32 v178, v64, v65
	v_cvt_pk_bf16_f32 v179, v66, v67
	v_add_u32_e32 v175, 0x42000, v155
	global_store_dwordx4 v175, v[176:179], s[64:65] nt
	v_mul_f32_e32 v158, 0xbfb8aa3b, v204
	v_mul_f32_e32 v160, v204, v204
	v_pk_mul_f32 v[162:163], v[60:61], v[158:159] op_sel_hi:[1,0]
	v_pk_mul_f32 v[164:165], v[62:63], v[158:159] op_sel_hi:[1,0]
	v_pk_mul_f32 v[166:167], v[52:53], v[158:159] op_sel_hi:[1,0]
	v_pk_mul_f32 v[168:169], v[54:55], v[158:159] op_sel_hi:[1,0]
	v_exp_f32_e32 v162, v162
	v_exp_f32_e32 v163, v163
	v_pk_mul_f32 v[56:57], v[60:61], v[56:57]
	v_exp_f32_e32 v164, v164
	v_exp_f32_e32 v165, v165
	v_pk_mul_f32 v[58:59], v[62:63], v[58:59]
	v_exp_f32_e32 v166, v166
	v_exp_f32_e32 v167, v167
	v_pk_mul_f32 v[48:49], v[52:53], v[48:49]
	v_exp_f32_e32 v168, v168
	v_exp_f32_e32 v169, v169
	v_pk_mul_f32 v[50:51], v[54:55], v[50:51]
	v_pk_add_f32 v[162:163], v[162:163], v[198:199] op_sel_hi:[1,0]
	v_pk_add_f32 v[164:165], v[164:165], v[198:199] op_sel_hi:[1,0]
	v_pk_add_f32 v[166:167], v[166:167], v[198:199] op_sel_hi:[1,0]
	v_pk_add_f32 v[168:169], v[168:169], v[198:199] op_sel_hi:[1,0]
	v_rcp_f32_e32 v162, v162
	v_rcp_f32_e32 v163, v163
	v_rcp_f32_e32 v164, v164
	v_rcp_f32_e32 v165, v165
	v_rcp_f32_e32 v166, v166
	v_rcp_f32_e32 v167, v167
	v_rcp_f32_e32 v168, v168
	v_rcp_f32_e32 v169, v169
	v_pk_mul_f32 v[162:163], v[160:161], v[162:163] op_sel_hi:[0,1]
	v_pk_mul_f32 v[164:165], v[160:161], v[164:165] op_sel_hi:[0,1]
	v_pk_mul_f32 v[166:167], v[160:161], v[166:167] op_sel_hi:[0,1]
	v_pk_mul_f32 v[168:169], v[160:161], v[168:169] op_sel_hi:[0,1]
	v_pk_mul_f32 v[56:57], v[56:57], v[162:163]
	v_pk_mul_f32 v[58:59], v[58:59], v[164:165]
	v_pk_mul_f32 v[48:49], v[48:49], v[166:167]
	v_pk_mul_f32 v[50:51], v[50:51], v[168:169]
	v_cvt_pk_bf16_f32 v170, v56, v57
	v_cvt_pk_bf16_f32 v171, v58, v59
	v_cvt_pk_bf16_f32 v172, v48, v49
	v_cvt_pk_bf16_f32 v173, v50, v51
	v_add_u32_e32 v174, 0xb0000, v155
	global_store_dwordx4 v174, v[170:173], s[64:65] nt
	v_mul_f32_e32 v158, 0xbfb8aa3b, v205
	v_mul_f32_e32 v160, v205, v205
	v_pk_mul_f32 v[162:163], v[44:45], v[158:159] op_sel_hi:[1,0]
	v_pk_mul_f32 v[164:165], v[46:47], v[158:159] op_sel_hi:[1,0]
	v_pk_mul_f32 v[166:167], v[36:37], v[158:159] op_sel_hi:[1,0]
	v_pk_mul_f32 v[168:169], v[38:39], v[158:159] op_sel_hi:[1,0]
	v_exp_f32_e32 v162, v162
	v_exp_f32_e32 v163, v163
	v_pk_mul_f32 v[40:41], v[44:45], v[40:41]
	v_exp_f32_e32 v164, v164
	v_exp_f32_e32 v165, v165
	v_pk_mul_f32 v[42:43], v[46:47], v[42:43]
	v_exp_f32_e32 v166, v166
	v_exp_f32_e32 v167, v167
	v_pk_mul_f32 v[32:33], v[36:37], v[32:33]
	v_exp_f32_e32 v168, v168
	v_exp_f32_e32 v169, v169
	v_pk_mul_f32 v[34:35], v[38:39], v[34:35]
	v_pk_add_f32 v[162:163], v[162:163], v[198:199] op_sel_hi:[1,0]
; __device__ __forceinline__ unsigned cvt_pk_bf16(float lo, float hi) { unsigned r; asm volatile("v_cvt_pk_bf16_f32 %0, %1, %2" : "=v"(r) : "v"(lo), "v"(hi)); return r; }
; #define PG8_BAR __builtin_amdgcn_s_barrier()
;     __device__ __forceinline__ void operator()(Acc& acc, const Unit& u, int wr, int wc, int fr, int fq) const {
;     ...
;             for (int m = 0; m < 4; ++m) {
;                 const int row = row0 + ai * HALF + m * 16;
;                 const float r = rs[u.idx * BM + wr * 64 + fr + ai * HALF + m * 16];
;                 const float c1 = -r * 1.4426950408889634f, r2 = r * r;
;                 f32x4 o[2];
; #pragma unroll
;                 for (int n = 0; n < 2; ++n) {
;                     const f32x4 g = acc[ai][0][m][n], up = acc[ai][1][m][n];
;                     const f32x4 t = g * c1; f32x4 e;
; #pragma unroll
;                     for (int i = 0; i < 4; ++i) e[i] = __builtin_amdgcn_exp2f(t[i]);
;                     const f32x4 d = e + 1.0f; f32x4 q;
; #pragma unroll
;                     for (int i = 0; i < 4; ++i) q[i] = __builtin_amdgcn_rcpf(d[i]);
;                     o[n] = (g * up) * (q * r2);
;                 }
;                 u32x4 w; w.x = cvt_pk_bf16(o[0][0], o[0][1]); w.y = cvt_pk_bf16(o[0][2], o[0][3]); w.z = cvt_pk_bf16(o[1][0], o[1][1]); w.w = cvt_pk_bf16(o[1][2], o[1][3]);
;                 *(u32x4*)(O + (size_t)row * DFF + col0) = w;
; template <class Epi, class Sched, bool ALIGN_EPI>
; __device__ __forceinline__ void gemm_phase(LAS unsigned char* lds, const Gemm g, const Sched& S, const Epi& E) {
;     ...
;         if (!has_next) break;
; #pragma unroll
;         for (int a = 0; a < 2; ++a)
; #pragma unroll
;             for (int b = 0; b < 2; ++b)
; #pragma unroll
;                 for (int m = 0; m < 4; ++m)
; #pragma unroll
;                     for (int n = 0; n < 2; ++n) acc[a][b][m][n] = (f32x4){0.f, 0.f, 0.f, 0.f};
;         cur = nxt; cA = nA; cB = nB; ++ui;
;         if constexpr (ALIGN_EPI) { if (wr == 1) PG8_BAR; }
	v_pk_add_f32 v[164:165], v[164:165], v[198:199] op_sel_hi:[1,0]
	v_pk_add_f32 v[166:167], v[166:167], v[198:199] op_sel_hi:[1,0]
	v_pk_add_f32 v[168:169], v[168:169], v[198:199] op_sel_hi:[1,0]
	v_rcp_f32_e32 v162, v162
	v_rcp_f32_e32 v163, v163
	v_rcp_f32_e32 v164, v164
	v_rcp_f32_e32 v165, v165
	v_rcp_f32_e32 v166, v166
	v_rcp_f32_e32 v167, v167
	v_rcp_f32_e32 v168, v168
	v_rcp_f32_e32 v169, v169
	v_pk_mul_f32 v[162:163], v[160:161], v[162:163] op_sel_hi:[0,1]
	v_pk_mul_f32 v[164:165], v[160:161], v[164:165] op_sel_hi:[0,1]
	v_pk_mul_f32 v[166:167], v[160:161], v[166:167] op_sel_hi:[0,1]
	v_pk_mul_f32 v[168:169], v[160:161], v[168:169] op_sel_hi:[0,1]
	v_pk_mul_f32 v[40:41], v[40:41], v[162:163]
	v_pk_mul_f32 v[42:43], v[42:43], v[164:165]
	v_pk_mul_f32 v[32:33], v[32:33], v[166:167]
	v_pk_mul_f32 v[34:35], v[34:35], v[168:169]
	v_cvt_pk_bf16_f32 v176, v40, v41
	v_cvt_pk_bf16_f32 v177, v42, v43
	v_cvt_pk_bf16_f32 v178, v32, v33
	v_cvt_pk_bf16_f32 v179, v34, v35
	v_add_u32_e32 v175, 0xc6000, v155
	global_store_dwordx4 v175, v[176:179], s[64:65] nt
	v_mul_f32_e32 v158, 0xbfb8aa3b, v206
	v_mul_f32_e32 v160, v206, v206
	v_pk_mul_f32 v[162:163], v[28:29], v[158:159] op_sel_hi:[1,0]
	v_pk_mul_f32 v[164:165], v[30:31], v[158:159] op_sel_hi:[1,0]
	v_pk_mul_f32 v[166:167], v[20:21], v[158:159] op_sel_hi:[1,0]
	v_pk_mul_f32 v[168:169], v[22:23], v[158:159] op_sel_hi:[1,0]
	v_exp_f32_e32 v162, v162
	v_exp_f32_e32 v163, v163
	v_pk_mul_f32 v[24:25], v[28:29], v[24:25]
	v_exp_f32_e32 v164, v164
	v_exp_f32_e32 v165, v165
	v_pk_mul_f32 v[26:27], v[30:31], v[26:27]
	v_exp_f32_e32 v166, v166
	v_exp_f32_e32 v167, v167
	v_pk_mul_f32 v[16:17], v[20:21], v[16:17]
	v_exp_f32_e32 v168, v168
	v_exp_f32_e32 v169, v169
	v_pk_mul_f32 v[18:19], v[22:23], v[18:19]
	v_pk_add_f32 v[162:163], v[162:163], v[198:199] op_sel_hi:[1,0]
	v_pk_add_f32 v[164:165], v[164:165], v[198:199] op_sel_hi:[1,0]
	v_pk_add_f32 v[166:167], v[166:167], v[198:199] op_sel_hi:[1,0]
	v_pk_add_f32 v[168:169], v[168:169], v[198:199] op_sel_hi:[1,0]
	v_rcp_f32_e32 v162, v162
	v_rcp_f32_e32 v163, v163
	v_rcp_f32_e32 v164, v164
	v_rcp_f32_e32 v165, v165
	v_rcp_f32_e32 v166, v166
	v_rcp_f32_e32 v167, v167
	v_rcp_f32_e32 v168, v168
	v_rcp_f32_e32 v169, v169
	v_pk_mul_f32 v[162:163], v[160:161], v[162:163] op_sel_hi:[0,1]
	v_pk_mul_f32 v[164:165], v[160:161], v[164:165] op_sel_hi:[0,1]
	v_pk_mul_f32 v[166:167], v[160:161], v[166:167] op_sel_hi:[0,1]
	v_pk_mul_f32 v[168:169], v[160:161], v[168:169] op_sel_hi:[0,1]
	v_pk_mul_f32 v[24:25], v[24:25], v[162:163]
	v_pk_mul_f32 v[26:27], v[26:27], v[164:165]
	v_pk_mul_f32 v[16:17], v[16:17], v[166:167]
	v_pk_mul_f32 v[18:19], v[18:19], v[168:169]
	v_cvt_pk_bf16_f32 v170, v24, v25
	v_cvt_pk_bf16_f32 v171, v26, v27
	v_cvt_pk_bf16_f32 v172, v16, v17
	v_cvt_pk_bf16_f32 v173, v18, v19
	v_add_u32_e32 v174, 0xdc000, v155
	global_store_dwordx4 v174, v[170:173], s[64:65] nt
	v_mul_f32_e32 v158, 0xbfb8aa3b, v207
	v_mul_f32_e32 v160, v207, v207
	v_pk_mul_f32 v[162:163], v[12:13], v[158:159] op_sel_hi:[1,0]
	v_pk_mul_f32 v[164:165], v[14:15], v[158:159] op_sel_hi:[1,0]
	v_pk_mul_f32 v[166:167], v[4:5], v[158:159] op_sel_hi:[1,0]
	v_pk_mul_f32 v[168:169], v[6:7], v[158:159] op_sel_hi:[1,0]
	v_exp_f32_e32 v162, v162
	v_exp_f32_e32 v163, v163
	v_pk_mul_f32 v[8:9], v[12:13], v[8:9]
	v_exp_f32_e32 v164, v164
	v_exp_f32_e32 v165, v165
	v_pk_mul_f32 v[10:11], v[14:15], v[10:11]
	v_exp_f32_e32 v166, v166
	v_exp_f32_e32 v167, v167
	v_pk_mul_f32 v[0:1], v[4:5], v[0:1]
	v_exp_f32_e32 v168, v168
	v_exp_f32_e32 v169, v169
	v_pk_mul_f32 v[2:3], v[6:7], v[2:3]
	v_pk_add_f32 v[162:163], v[162:163], v[198:199] op_sel_hi:[1,0]
	v_pk_add_f32 v[164:165], v[164:165], v[198:199] op_sel_hi:[1,0]
	v_pk_add_f32 v[166:167], v[166:167], v[198:199] op_sel_hi:[1,0]
	v_pk_add_f32 v[168:169], v[168:169], v[198:199] op_sel_hi:[1,0]
	v_rcp_f32_e32 v162, v162
	v_rcp_f32_e32 v163, v163
	v_rcp_f32_e32 v164, v164
	v_rcp_f32_e32 v165, v165
	v_rcp_f32_e32 v166, v166
	v_rcp_f32_e32 v167, v167
	v_rcp_f32_e32 v168, v168
	v_rcp_f32_e32 v169, v169
	v_pk_mul_f32 v[162:163], v[160:161], v[162:163] op_sel_hi:[0,1]
	v_pk_mul_f32 v[164:165], v[160:161], v[164:165] op_sel_hi:[0,1]
	v_pk_mul_f32 v[166:167], v[160:161], v[166:167] op_sel_hi:[0,1]
	v_pk_mul_f32 v[168:169], v[160:161], v[168:169] op_sel_hi:[0,1]
	v_pk_mul_f32 v[8:9], v[8:9], v[162:163]
	v_pk_mul_f32 v[10:11], v[10:11], v[164:165]
	v_pk_mul_f32 v[0:1], v[0:1], v[166:167]
	v_pk_mul_f32 v[2:3], v[2:3], v[168:169]
	v_cvt_pk_bf16_f32 v176, v8, v9
	v_cvt_pk_bf16_f32 v177, v10, v11
	v_cvt_pk_bf16_f32 v178, v0, v1
	v_cvt_pk_bf16_f32 v179, v2, v3
	v_add_u32_e32 v175, 0xf2000, v155
	global_store_dwordx4 v175, v[176:179], s[64:65] nt
	s_andn2_b64 vcc, exec, s[2:3]
	s_mov_b64 s[2:3], -1
	s_mov_b32 s101, 1
	s_cbranch_vccnz .LBB0_1609
	s_andn2_b64 vcc, exec, s[4:5]
	s_cbranch_vccnz .LBB0_1608
	s_barrier
	s_branch .LBB0_1608
